# load segments of the 4 big GEMM mainloops run at s_setprio 2 (MFMA segments stay at 1)
# speedup vs baseline: 1.0152x; 1.0109x over previous
.LBB0_195:
	ds_read_b128 v[128:131], v179
	ds_read_b128 v[132:135], v179 offset:1024
	ds_read_b128 v[136:139], v179 offset:2048
	ds_read_b128 v[162:165], v179 offset:3072
	ds_read_b128 v[166:169], v180
	ds_read_b128 v[170:173], v180 offset:1024
	ds_read_b128 v[194:197], v180 offset:2048
	ds_read_b128 v[198:201], v180 offset:3072
	s_add_u32 s2, s8, 0xfff80080
	s_addc_u32 s3, s9, -1
	s_cmp_eq_u32 s66, 28
	s_cselect_b32 s65, s0, s3
	s_cselect_b32 s64, s30, s2
	s_cselect_b32 s61, s31, s57
	s_cselect_b32 s60, s39, s41
	s_add_i32 m0, s72, 0xc000
	ds_read_b128 v[202:205], v181
	ds_read_b128 v[206:209], v181 offset:1024
	ds_read_b128 v[210:213], v181 offset:2048
	ds_read_b128 v[214:217], v181 offset:3072
	ds_read_b128 v[218:221], v181 offset:4096
	ds_read_b128 v[222:225], v181 offset:5120
	ds_read_b128 v[226:229], v181 offset:6144
	ds_read_b128 v[230:233], v181 offset:7168
	global_load_lds_dwordx4 v154, s[8:9]
	s_add_i32 m0, s72, 0xe000
	s_nop 0
	global_load_lds_dwordx4 v156, s[8:9]
	s_waitcnt vmcnt(8)
	s_waitcnt lgkmcnt(0)
	s_barrier
	s_setprio 1
	s_waitcnt lgkmcnt(0)
	v_mfma_f32_16x16x32_bf16 v[124:127], v[128:131], v[202:205], v[124:127]
	v_mfma_f32_16x16x32_bf16 v[120:123], v[136:139], v[202:205], v[120:123]
	v_mfma_f32_16x16x32_bf16 v[116:119], v[128:131], v[210:213], v[116:119]
	v_mfma_f32_16x16x32_bf16 v[112:115], v[136:139], v[210:213], v[112:115]
	v_mfma_f32_16x16x32_bf16 v[108:111], v[128:131], v[218:221], v[108:111]
	v_mfma_f32_16x16x32_bf16 v[104:107], v[136:139], v[218:221], v[104:107]
	v_mfma_f32_16x16x32_bf16 v[100:103], v[128:131], v[226:229], v[100:103]
	v_mfma_f32_16x16x32_bf16 v[96:99], v[136:139], v[226:229], v[96:99]
	v_mfma_f32_16x16x32_bf16 v[124:127], v[132:135], v[206:209], v[124:127]
	v_mfma_f32_16x16x32_bf16 v[120:123], v[162:165], v[206:209], v[120:123]
	v_mfma_f32_16x16x32_bf16 v[116:119], v[132:135], v[214:217], v[116:119]
	v_mfma_f32_16x16x32_bf16 v[112:115], v[162:165], v[214:217], v[112:115]
	v_mfma_f32_16x16x32_bf16 v[108:111], v[132:135], v[222:225], v[108:111]
	v_mfma_f32_16x16x32_bf16 v[104:107], v[162:165], v[222:225], v[104:107]
	v_mfma_f32_16x16x32_bf16 v[100:103], v[132:135], v[230:233], v[100:103]
	v_mfma_f32_16x16x32_bf16 v[96:99], v[162:165], v[230:233], v[96:99]
	s_setprio 0
	s_setprio 1
	v_mfma_f32_16x16x32_bf16 v[60:63], v[166:169], v[202:205], v[60:63]
	v_mfma_f32_16x16x32_bf16 v[56:59], v[194:197], v[202:205], v[56:59]
	v_mfma_f32_16x16x32_bf16 v[52:55], v[166:169], v[210:213], v[52:55]
	v_mfma_f32_16x16x32_bf16 v[48:51], v[194:197], v[210:213], v[48:51]
	v_mfma_f32_16x16x32_bf16 v[44:47], v[166:169], v[218:221], v[44:47]
	v_mfma_f32_16x16x32_bf16 v[40:43], v[194:197], v[218:221], v[40:43]
	v_mfma_f32_16x16x32_bf16 v[36:39], v[166:169], v[226:229], v[36:39]
	v_mfma_f32_16x16x32_bf16 v[32:35], v[194:197], v[226:229], v[32:35]
	v_mfma_f32_16x16x32_bf16 v[60:63], v[170:173], v[206:209], v[60:63]
	v_mfma_f32_16x16x32_bf16 v[56:59], v[198:201], v[206:209], v[56:59]
	v_mfma_f32_16x16x32_bf16 v[52:55], v[170:173], v[214:217], v[52:55]
	v_mfma_f32_16x16x32_bf16 v[48:51], v[198:201], v[214:217], v[48:51]
	v_mfma_f32_16x16x32_bf16 v[44:47], v[170:173], v[222:225], v[44:47]
	v_mfma_f32_16x16x32_bf16 v[40:43], v[198:201], v[222:225], v[40:43]
	v_mfma_f32_16x16x32_bf16 v[36:39], v[170:173], v[230:233], v[36:39]
	v_mfma_f32_16x16x32_bf16 v[32:35], v[198:201], v[230:233], v[32:35]
	s_setprio 2
	s_barrier
	s_add_i32 s2, s81, s35
	s_mov_b32 m0, s2
	ds_read_b128 v[202:205], v181 offset:16384
	ds_read_b128 v[206:209], v181 offset:17408
	ds_read_b128 v[210:213], v181 offset:18432
	ds_read_b128 v[214:217], v181 offset:19456
	ds_read_b128 v[218:221], v181 offset:20480
	ds_read_b128 v[222:225], v181 offset:21504
	ds_read_b128 v[226:229], v181 offset:22528
	ds_read_b128 v[230:233], v181 offset:23552
	global_load_lds_dwordx4 v142, s[60:61]
	s_add_i32 m0, s2, 0x2000
	s_add_u32 s2, s60, 0x80000
	s_addc_u32 s3, s61, 0
	s_add_i32 s46, s82, s35
	global_load_lds_dwordx4 v146, s[60:61]
	s_mov_b32 m0, s46
	s_nop 0
	global_load_lds_dwordx4 v142, s[2:3]
	s_add_i32 m0, s46, 0x2000
	s_nop 0
	global_load_lds_dwordx4 v146, s[2:3]
	s_mov_b32 m0, s72
	s_nop 0
	global_load_lds_dwordx4 v140, s[64:65]
	s_mov_b32 m0, s73
	s_nop 0
	global_load_lds_dwordx4 v144, s[64:65]
	s_waitcnt vmcnt(8)
	s_waitcnt lgkmcnt(0)
	s_barrier
	s_setprio 1
	s_waitcnt lgkmcnt(0)
	v_mfma_f32_16x16x32_bf16 v[92:95], v[128:131], v[202:205], v[92:95]
	v_mfma_f32_16x16x32_bf16 v[88:91], v[136:139], v[202:205], v[88:91]
	v_mfma_f32_16x16x32_bf16 v[84:87], v[128:131], v[210:213], v[84:87]
	v_mfma_f32_16x16x32_bf16 v[80:83], v[136:139], v[210:213], v[80:83]
	v_mfma_f32_16x16x32_bf16 v[76:79], v[128:131], v[218:221], v[76:79]
	v_mfma_f32_16x16x32_bf16 v[72:75], v[136:139], v[218:221], v[72:75]
	v_mfma_f32_16x16x32_bf16 v[68:71], v[128:131], v[226:229], v[68:71]
	v_mfma_f32_16x16x32_bf16 v[64:67], v[136:139], v[226:229], v[64:67]
	v_mfma_f32_16x16x32_bf16 v[92:95], v[132:135], v[206:209], v[92:95]
	v_mfma_f32_16x16x32_bf16 v[88:91], v[162:165], v[206:209], v[88:91]
	v_mfma_f32_16x16x32_bf16 v[84:87], v[132:135], v[214:217], v[84:87]
	v_mfma_f32_16x16x32_bf16 v[80:83], v[162:165], v[214:217], v[80:83]
	v_mfma_f32_16x16x32_bf16 v[76:79], v[132:135], v[222:225], v[76:79]
	v_mfma_f32_16x16x32_bf16 v[72:75], v[162:165], v[222:225], v[72:75]
	v_mfma_f32_16x16x32_bf16 v[68:71], v[132:135], v[230:233], v[68:71]
	v_mfma_f32_16x16x32_bf16 v[64:67], v[162:165], v[230:233], v[64:67]
	s_setprio 0
	s_setprio 1
	v_mfma_f32_16x16x32_bf16 v[28:31], v[166:169], v[202:205], v[28:31]
	v_mfma_f32_16x16x32_bf16 v[24:27], v[194:197], v[202:205], v[24:27]
	v_mfma_f32_16x16x32_bf16 v[20:23], v[166:169], v[210:213], v[20:23]
	v_mfma_f32_16x16x32_bf16 v[16:19], v[194:197], v[210:213], v[16:19]
	v_mfma_f32_16x16x32_bf16 v[12:15], v[166:169], v[218:221], v[12:15]
	v_mfma_f32_16x16x32_bf16 v[8:11], v[194:197], v[218:221], v[8:11]
	v_mfma_f32_16x16x32_bf16 v[4:7], v[166:169], v[226:229], v[4:7]
	v_mfma_f32_16x16x32_bf16 v[0:3], v[194:197], v[226:229], v[0:3]
	v_mfma_f32_16x16x32_bf16 v[28:31], v[170:173], v[206:209], v[28:31]
	v_mfma_f32_16x16x32_bf16 v[24:27], v[198:201], v[206:209], v[24:27]
	v_mfma_f32_16x16x32_bf16 v[20:23], v[170:173], v[214:217], v[20:23]
	v_mfma_f32_16x16x32_bf16 v[16:19], v[198:201], v[214:217], v[16:19]
	v_mfma_f32_16x16x32_bf16 v[12:15], v[170:173], v[222:225], v[12:15]
	v_mfma_f32_16x16x32_bf16 v[8:11], v[198:201], v[222:225], v[8:11]
	v_mfma_f32_16x16x32_bf16 v[4:7], v[170:173], v[230:233], v[4:7]
	v_mfma_f32_16x16x32_bf16 v[0:3], v[198:201], v[230:233], v[0:3]
	s_setprio 2
	s_barrier
	s_add_i32 s46, 0, 0x18000
	v_add_u32_e32 v148, s46, v174
	s_add_i32 s47, 0, 0x1c000
	ds_read_b128 v[128:131], v148
	ds_read_b128 v[132:135], v148 offset:1024
	ds_read_b128 v[136:139], v148 offset:2048
	ds_read_b128 v[162:165], v148 offset:3072
	v_add_u32_e32 v148, s47, v174
	ds_read_b128 v[166:169], v148
	ds_read_b128 v[170:173], v148 offset:1024
	ds_read_b128 v[194:197], v148 offset:2048
	ds_read_b128 v[198:201], v148 offset:3072
	s_add_u32 s2, s64, 0x80000
	s_addc_u32 s3, s65, 0
	s_mov_b32 m0, s74
	ds_read_b128 v[202:205], v181 offset:32768
	ds_read_b128 v[206:209], v181 offset:33792
	ds_read_b128 v[210:213], v181 offset:34816
	ds_read_b128 v[214:217], v181 offset:35840
	ds_read_b128 v[218:221], v181 offset:36864
	ds_read_b128 v[222:225], v181 offset:37888
	ds_read_b128 v[226:229], v181 offset:38912
	ds_read_b128 v[230:233], v181 offset:39936
	global_load_lds_dwordx4 v140, s[2:3]
	s_mov_b32 m0, s75
	s_nop 0
	global_load_lds_dwordx4 v144, s[2:3]
	s_waitcnt vmcnt(8)
	s_waitcnt lgkmcnt(0)
	s_barrier
	s_setprio 1
	s_waitcnt lgkmcnt(0)
	v_mfma_f32_16x16x32_bf16 v[124:127], v[128:131], v[202:205], v[124:127]
	v_mfma_f32_16x16x32_bf16 v[120:123], v[136:139], v[202:205], v[120:123]
	v_mfma_f32_16x16x32_bf16 v[116:119], v[128:131], v[210:213], v[116:119]
	v_mfma_f32_16x16x32_bf16 v[112:115], v[136:139], v[210:213], v[112:115]
	v_mfma_f32_16x16x32_bf16 v[108:111], v[128:131], v[218:221], v[108:111]
	v_mfma_f32_16x16x32_bf16 v[104:107], v[136:139], v[218:221], v[104:107]
	v_mfma_f32_16x16x32_bf16 v[100:103], v[128:131], v[226:229], v[100:103]
	v_mfma_f32_16x16x32_bf16 v[96:99], v[136:139], v[226:229], v[96:99]
	v_mfma_f32_16x16x32_bf16 v[124:127], v[132:135], v[206:209], v[124:127]
	v_mfma_f32_16x16x32_bf16 v[120:123], v[162:165], v[206:209], v[120:123]
	v_mfma_f32_16x16x32_bf16 v[116:119], v[132:135], v[214:217], v[116:119]
	v_mfma_f32_16x16x32_bf16 v[112:115], v[162:165], v[214:217], v[112:115]
	v_mfma_f32_16x16x32_bf16 v[108:111], v[132:135], v[222:225], v[108:111]
	v_mfma_f32_16x16x32_bf16 v[104:107], v[162:165], v[222:225], v[104:107]
	v_mfma_f32_16x16x32_bf16 v[100:103], v[132:135], v[230:233], v[100:103]
	v_mfma_f32_16x16x32_bf16 v[96:99], v[162:165], v[230:233], v[96:99]
	s_setprio 0
	s_setprio 1
	v_mfma_f32_16x16x32_bf16 v[60:63], v[166:169], v[202:205], v[60:63]
	v_mfma_f32_16x16x32_bf16 v[56:59], v[194:197], v[202:205], v[56:59]
	v_mfma_f32_16x16x32_bf16 v[52:55], v[166:169], v[210:213], v[52:55]
	v_mfma_f32_16x16x32_bf16 v[48:51], v[194:197], v[210:213], v[48:51]
	v_mfma_f32_16x16x32_bf16 v[44:47], v[166:169], v[218:221], v[44:47]
	v_mfma_f32_16x16x32_bf16 v[40:43], v[194:197], v[218:221], v[40:43]
	v_mfma_f32_16x16x32_bf16 v[36:39], v[166:169], v[226:229], v[36:39]
	v_mfma_f32_16x16x32_bf16 v[32:35], v[194:197], v[226:229], v[32:35]
	v_mfma_f32_16x16x32_bf16 v[60:63], v[170:173], v[206:209], v[60:63]
	v_mfma_f32_16x16x32_bf16 v[56:59], v[198:201], v[206:209], v[56:59]
	v_mfma_f32_16x16x32_bf16 v[52:55], v[170:173], v[214:217], v[52:55]
	v_mfma_f32_16x16x32_bf16 v[48:51], v[198:201], v[214:217], v[48:51]
	v_mfma_f32_16x16x32_bf16 v[44:47], v[170:173], v[222:225], v[44:47]
	v_mfma_f32_16x16x32_bf16 v[40:43], v[198:201], v[222:225], v[40:43]
	v_mfma_f32_16x16x32_bf16 v[36:39], v[170:173], v[230:233], v[36:39]
	v_mfma_f32_16x16x32_bf16 v[32:35], v[198:201], v[230:233], v[32:35]
	s_setprio 2
	s_barrier
	s_add_i32 s2, s46, s35
	s_add_i32 m0, s2, 0xffffff80
	ds_read_b128 v[202:205], v181 offset:49152
	ds_read_b128 v[206:209], v181 offset:50176
	ds_read_b128 v[210:213], v181 offset:51200
	ds_read_b128 v[214:217], v181 offset:52224
	ds_read_b128 v[218:221], v181 offset:53248
	ds_read_b128 v[222:225], v181 offset:54272
	ds_read_b128 v[226:229], v181 offset:55296
	ds_read_b128 v[230:233], v181 offset:56320
	global_load_lds_dwordx4 v142, s[60:61] offset:128
	s_add_i32 m0, s2, 0x1f80
	s_add_u32 s2, s60, 0x80080
	s_addc_u32 s3, s61, 0
	s_add_i32 s46, s47, s35
	global_load_lds_dwordx4 v146, s[60:61] offset:128
	s_mov_b32 m0, s46
	s_nop 0
	global_load_lds_dwordx4 v142, s[2:3]
	s_add_i32 m0, s46, 0x2000
	s_nop 0
	global_load_lds_dwordx4 v146, s[2:3]
	s_add_i32 m0, s76, 0xffffff80
	s_nop 0
	global_load_lds_dwordx4 v140, s[64:65] offset:128
	s_add_i32 m0, s77, 0xffffff80
	s_nop 0
	global_load_lds_dwordx4 v144, s[64:65] offset:128
	s_waitcnt vmcnt(8)
	s_waitcnt lgkmcnt(0)
	s_barrier
	s_setprio 1
	s_waitcnt lgkmcnt(0)
	v_mfma_f32_16x16x32_bf16 v[92:95], v[128:131], v[202:205], v[92:95]
	v_mfma_f32_16x16x32_bf16 v[88:91], v[136:139], v[202:205], v[88:91]
	v_mfma_f32_16x16x32_bf16 v[84:87], v[128:131], v[210:213], v[84:87]
	v_mfma_f32_16x16x32_bf16 v[80:83], v[136:139], v[210:213], v[80:83]
	v_mfma_f32_16x16x32_bf16 v[76:79], v[128:131], v[218:221], v[76:79]
	v_mfma_f32_16x16x32_bf16 v[72:75], v[136:139], v[218:221], v[72:75]
	v_mfma_f32_16x16x32_bf16 v[68:71], v[128:131], v[226:229], v[68:71]
	v_mfma_f32_16x16x32_bf16 v[64:67], v[136:139], v[226:229], v[64:67]
	v_mfma_f32_16x16x32_bf16 v[92:95], v[132:135], v[206:209], v[92:95]
	v_mfma_f32_16x16x32_bf16 v[88:91], v[162:165], v[206:209], v[88:91]
	v_mfma_f32_16x16x32_bf16 v[84:87], v[132:135], v[214:217], v[84:87]
	v_mfma_f32_16x16x32_bf16 v[80:83], v[162:165], v[214:217], v[80:83]
	v_mfma_f32_16x16x32_bf16 v[76:79], v[132:135], v[222:225], v[76:79]
	v_mfma_f32_16x16x32_bf16 v[72:75], v[162:165], v[222:225], v[72:75]
	v_mfma_f32_16x16x32_bf16 v[68:71], v[132:135], v[230:233], v[68:71]
	v_mfma_f32_16x16x32_bf16 v[64:67], v[162:165], v[230:233], v[64:67]
	s_setprio 0
	s_setprio 1
	v_mfma_f32_16x16x32_bf16 v[28:31], v[166:169], v[202:205], v[28:31]
	v_mfma_f32_16x16x32_bf16 v[24:27], v[194:197], v[202:205], v[24:27]
	v_mfma_f32_16x16x32_bf16 v[20:23], v[166:169], v[210:213], v[20:23]
	v_mfma_f32_16x16x32_bf16 v[16:19], v[194:197], v[210:213], v[16:19]
	v_mfma_f32_16x16x32_bf16 v[12:15], v[166:169], v[218:221], v[12:15]
	v_mfma_f32_16x16x32_bf16 v[8:11], v[194:197], v[218:221], v[8:11]
	v_mfma_f32_16x16x32_bf16 v[4:7], v[166:169], v[226:229], v[4:7]
	v_mfma_f32_16x16x32_bf16 v[0:3], v[194:197], v[226:229], v[0:3]
	v_mfma_f32_16x16x32_bf16 v[28:31], v[170:173], v[206:209], v[28:31]
	v_mfma_f32_16x16x32_bf16 v[24:27], v[198:201], v[206:209], v[24:27]
	v_mfma_f32_16x16x32_bf16 v[20:23], v[170:173], v[214:217], v[20:23]
	v_mfma_f32_16x16x32_bf16 v[16:19], v[198:201], v[214:217], v[16:19]
	v_mfma_f32_16x16x32_bf16 v[12:15], v[170:173], v[222:225], v[12:15]
	v_mfma_f32_16x16x32_bf16 v[8:11], v[198:201], v[222:225], v[8:11]
	v_mfma_f32_16x16x32_bf16 v[4:7], v[170:173], v[230:233], v[4:7]
	v_mfma_f32_16x16x32_bf16 v[0:3], v[198:201], v[230:233], v[0:3]
	s_setprio 2
	s_barrier
	s_add_i32 s66, s66, 2
	s_add_u32 s8, s8, 0x100
	s_addc_u32 s9, s9, 0
	s_add_u32 s41, s41, 0x100
	s_addc_u32 s57, s57, 0
	s_cmp_gt_u32 s66, 29
	s_cbranch_scc0 .LBB0_195
	s_and_b64 vcc, exec, s[16:17]
	s_cbranch_vccz .LBB0_198
	s_barrier

.LBB0_497:
	ds_read_b128 v[146:149], v153
	ds_read_b128 v[156:159], v153 offset:1024
	ds_read_b128 v[160:163], v153 offset:2048
	ds_read_b128 v[164:167], v153 offset:3072
	ds_read_b128 v[168:171], v154
	ds_read_b128 v[172:175], v154 offset:1024
	ds_read_b128 v[176:179], v154 offset:2048
	ds_read_b128 v[180:183], v154 offset:3072
	s_add_u32 s2, s56, 0xfff80080
	s_addc_u32 s3, s57, -1
	s_cmp_eq_u32 s77, 28
	s_cselect_b32 s65, s30, s3
	s_cselect_b32 s64, s31, s2
	s_cselect_b32 s61, s37, s76
	s_cselect_b32 s60, s39, s51
	v_lshl_add_u64 v[150:151], s[56:57], 0, v[138:139]
	s_add_i32 m0, s34, 0xc000
	ds_read_b128 v[184:187], v155
	ds_read_b128 v[192:195], v155 offset:1024
	ds_read_b128 v[196:199], v155 offset:2048
	ds_read_b128 v[200:203], v155 offset:3072
	ds_read_b128 v[204:207], v155 offset:4096
	ds_read_b128 v[208:211], v155 offset:5120
	ds_read_b128 v[212:215], v155 offset:6144
	ds_read_b128 v[216:219], v155 offset:7168
	global_load_lds_dwordx4 v[150:151], off
	v_lshl_add_u64 v[150:151], s[56:57], 0, v[140:141]
	s_add_i32 m0, s34, 0xe000
	s_nop 0
	global_load_lds_dwordx4 v[150:151], off
	s_waitcnt vmcnt(8)
	s_waitcnt lgkmcnt(0)
	s_barrier
	s_setprio 1
	s_waitcnt lgkmcnt(0)
	v_mfma_f32_16x16x32_bf16 v[124:127], v[146:149], v[184:187], v[124:127]
	v_mfma_f32_16x16x32_bf16 v[120:123], v[160:163], v[184:187], v[120:123]
	v_mfma_f32_16x16x32_bf16 v[108:111], v[146:149], v[196:199], v[108:111]
	v_mfma_f32_16x16x32_bf16 v[104:107], v[160:163], v[196:199], v[104:107]
	v_mfma_f32_16x16x32_bf16 v[92:95], v[146:149], v[204:207], v[92:95]
	v_mfma_f32_16x16x32_bf16 v[88:91], v[160:163], v[204:207], v[88:91]
	v_mfma_f32_16x16x32_bf16 v[76:79], v[146:149], v[212:215], v[76:79]
	v_mfma_f32_16x16x32_bf16 v[72:75], v[160:163], v[212:215], v[72:75]
	v_mfma_f32_16x16x32_bf16 v[124:127], v[156:159], v[192:195], v[124:127]
	v_mfma_f32_16x16x32_bf16 v[120:123], v[164:167], v[192:195], v[120:123]
	v_mfma_f32_16x16x32_bf16 v[108:111], v[156:159], v[200:203], v[108:111]
	v_mfma_f32_16x16x32_bf16 v[104:107], v[164:167], v[200:203], v[104:107]
	v_mfma_f32_16x16x32_bf16 v[92:95], v[156:159], v[208:211], v[92:95]
	v_mfma_f32_16x16x32_bf16 v[88:91], v[164:167], v[208:211], v[88:91]
	v_mfma_f32_16x16x32_bf16 v[76:79], v[156:159], v[216:219], v[76:79]
	v_mfma_f32_16x16x32_bf16 v[72:75], v[164:167], v[216:219], v[72:75]
	s_setprio 0
	s_setprio 1
	v_mfma_f32_16x16x32_bf16 v[116:119], v[168:171], v[184:187], v[116:119]
	v_mfma_f32_16x16x32_bf16 v[112:115], v[176:179], v[184:187], v[112:115]
	v_mfma_f32_16x16x32_bf16 v[100:103], v[168:171], v[196:199], v[100:103]
	v_mfma_f32_16x16x32_bf16 v[96:99], v[176:179], v[196:199], v[96:99]
	v_mfma_f32_16x16x32_bf16 v[84:87], v[168:171], v[204:207], v[84:87]
	v_mfma_f32_16x16x32_bf16 v[80:83], v[176:179], v[204:207], v[80:83]
	v_mfma_f32_16x16x32_bf16 v[68:71], v[168:171], v[212:215], v[68:71]
	v_mfma_f32_16x16x32_bf16 v[64:67], v[176:179], v[212:215], v[64:67]
	v_mfma_f32_16x16x32_bf16 v[116:119], v[172:175], v[192:195], v[116:119]
	v_mfma_f32_16x16x32_bf16 v[112:115], v[180:183], v[192:195], v[112:115]
	v_mfma_f32_16x16x32_bf16 v[100:103], v[172:175], v[200:203], v[100:103]
	v_mfma_f32_16x16x32_bf16 v[96:99], v[180:183], v[200:203], v[96:99]
	v_mfma_f32_16x16x32_bf16 v[84:87], v[172:175], v[208:211], v[84:87]
	v_mfma_f32_16x16x32_bf16 v[80:83], v[180:183], v[208:211], v[80:83]
	v_mfma_f32_16x16x32_bf16 v[68:71], v[172:175], v[216:219], v[68:71]
	v_mfma_f32_16x16x32_bf16 v[64:67], v[180:183], v[216:219], v[64:67]
	s_setprio 2
	s_barrier
	s_add_i32 s2, s73, s33
	v_lshl_add_u64 v[150:151], s[60:61], 0, v[130:131]
	s_mov_b32 m0, s2
	ds_read_b128 v[184:187], v155 offset:16384
	ds_read_b128 v[192:195], v155 offset:17408
	ds_read_b128 v[196:199], v155 offset:18432
	ds_read_b128 v[200:203], v155 offset:19456
	ds_read_b128 v[204:207], v155 offset:20480
	ds_read_b128 v[208:211], v155 offset:21504
	ds_read_b128 v[212:215], v155 offset:22528
	ds_read_b128 v[216:219], v155 offset:23552
	global_load_lds_dwordx4 v[150:151], off
	s_add_i32 m0, s2, 0x2000
	s_add_u32 s2, s60, 0x80000
	v_lshl_add_u64 v[220:221], s[60:61], 0, v[134:135]
	s_addc_u32 s3, s61, 0
	s_add_i32 s46, s74, s33
	global_load_lds_dwordx4 v[220:221], off
	v_lshl_add_u64 v[222:223], s[2:3], 0, v[130:131]
	s_mov_b32 m0, s46
	v_lshl_add_u64 v[224:225], s[64:65], 0, v[132:133]
	global_load_lds_dwordx4 v[222:223], off
	v_lshl_add_u64 v[222:223], s[2:3], 0, v[134:135]
	s_add_i32 m0, s46, 0x2000
	s_nop 0
	global_load_lds_dwordx4 v[222:223], off
	v_lshl_add_u64 v[222:223], s[64:65], 0, v[128:129]
	s_mov_b32 m0, s34
	s_nop 0
	global_load_lds_dwordx4 v[222:223], off
	s_mov_b32 m0, s35
	s_nop 0
	global_load_lds_dwordx4 v[224:225], off
	s_waitcnt vmcnt(8)
	s_waitcnt lgkmcnt(0)
	s_barrier
	s_setprio 1
	s_waitcnt lgkmcnt(0)
	v_mfma_f32_16x16x32_bf16 v[60:63], v[146:149], v[184:187], v[60:63]
	v_mfma_f32_16x16x32_bf16 v[56:59], v[160:163], v[184:187], v[56:59]
	v_mfma_f32_16x16x32_bf16 v[44:47], v[146:149], v[196:199], v[44:47]
	v_mfma_f32_16x16x32_bf16 v[40:43], v[160:163], v[196:199], v[40:43]
	v_mfma_f32_16x16x32_bf16 v[28:31], v[146:149], v[204:207], v[28:31]
	v_mfma_f32_16x16x32_bf16 v[24:27], v[160:163], v[204:207], v[24:27]
	v_mfma_f32_16x16x32_bf16 v[12:15], v[146:149], v[212:215], v[12:15]
	v_mfma_f32_16x16x32_bf16 v[8:11], v[160:163], v[212:215], v[8:11]
	v_mfma_f32_16x16x32_bf16 v[60:63], v[156:159], v[192:195], v[60:63]
	v_mfma_f32_16x16x32_bf16 v[56:59], v[164:167], v[192:195], v[56:59]
	v_mfma_f32_16x16x32_bf16 v[44:47], v[156:159], v[200:203], v[44:47]
	v_mfma_f32_16x16x32_bf16 v[40:43], v[164:167], v[200:203], v[40:43]
	v_mfma_f32_16x16x32_bf16 v[28:31], v[156:159], v[208:211], v[28:31]
	v_mfma_f32_16x16x32_bf16 v[24:27], v[164:167], v[208:211], v[24:27]
	v_mfma_f32_16x16x32_bf16 v[12:15], v[156:159], v[216:219], v[12:15]
	v_mfma_f32_16x16x32_bf16 v[8:11], v[164:167], v[216:219], v[8:11]
	s_setprio 0
	s_setprio 1
	v_mfma_f32_16x16x32_bf16 v[52:55], v[168:171], v[184:187], v[52:55]
	v_mfma_f32_16x16x32_bf16 v[48:51], v[176:179], v[184:187], v[48:51]
	v_mfma_f32_16x16x32_bf16 v[36:39], v[168:171], v[196:199], v[36:39]
	v_mfma_f32_16x16x32_bf16 v[32:35], v[176:179], v[196:199], v[32:35]
	v_mfma_f32_16x16x32_bf16 v[20:23], v[168:171], v[204:207], v[20:23]
	v_mfma_f32_16x16x32_bf16 v[16:19], v[176:179], v[204:207], v[16:19]
	v_mfma_f32_16x16x32_bf16 v[4:7], v[168:171], v[212:215], v[4:7]
	v_mfma_f32_16x16x32_bf16 v[0:3], v[176:179], v[212:215], v[0:3]
	v_mfma_f32_16x16x32_bf16 v[52:55], v[172:175], v[192:195], v[52:55]
	v_mfma_f32_16x16x32_bf16 v[48:51], v[180:183], v[192:195], v[48:51]
	v_mfma_f32_16x16x32_bf16 v[36:39], v[172:175], v[200:203], v[36:39]
	v_mfma_f32_16x16x32_bf16 v[32:35], v[180:183], v[200:203], v[32:35]
	v_mfma_f32_16x16x32_bf16 v[20:23], v[172:175], v[208:211], v[20:23]
	v_mfma_f32_16x16x32_bf16 v[16:19], v[180:183], v[208:211], v[16:19]
	v_mfma_f32_16x16x32_bf16 v[4:7], v[172:175], v[216:219], v[4:7]
	v_mfma_f32_16x16x32_bf16 v[0:3], v[180:183], v[216:219], v[0:3]
	s_setprio 2
	s_barrier
	s_add_i32 s46, 0, 0x18000
	s_add_i32 s47, 0, 0x1c000
	v_add_u32_e32 v164, s46, v152
	v_add_u32_e32 v180, s47, v152
	ds_read_b128 v[146:149], v164
	ds_read_b128 v[156:159], v164 offset:1024
	ds_read_b128 v[160:163], v164 offset:2048
	ds_read_b128 v[164:167], v164 offset:3072
	ds_read_b128 v[168:171], v180
	ds_read_b128 v[172:175], v180 offset:1024
	ds_read_b128 v[176:179], v180 offset:2048
	ds_read_b128 v[180:183], v180 offset:3072
	s_add_u32 s2, s64, 0x80000
	s_addc_u32 s3, s65, 0
	s_mov_b32 m0, s66
	v_lshl_add_u64 v[226:227], s[2:3], 0, v[128:129]
	ds_read_b128 v[184:187], v155 offset:32768
	ds_read_b128 v[192:195], v155 offset:33792
	ds_read_b128 v[196:199], v155 offset:34816
	ds_read_b128 v[200:203], v155 offset:35840
	ds_read_b128 v[204:207], v155 offset:36864
	ds_read_b128 v[208:211], v155 offset:37888
	ds_read_b128 v[212:215], v155 offset:38912
	ds_read_b128 v[216:219], v155 offset:39936
	global_load_lds_dwordx4 v[226:227], off
	v_lshl_add_u64 v[226:227], s[2:3], 0, v[132:133]
	s_mov_b32 m0, s67
	s_nop 0
	global_load_lds_dwordx4 v[226:227], off
	s_waitcnt vmcnt(8)
	s_waitcnt lgkmcnt(0)
	s_barrier
	s_setprio 1
	s_waitcnt lgkmcnt(0)
	v_mfma_f32_16x16x32_bf16 v[124:127], v[146:149], v[184:187], v[124:127]
	v_mfma_f32_16x16x32_bf16 v[120:123], v[160:163], v[184:187], v[120:123]
	v_mfma_f32_16x16x32_bf16 v[108:111], v[146:149], v[196:199], v[108:111]
	v_mfma_f32_16x16x32_bf16 v[104:107], v[160:163], v[196:199], v[104:107]
	v_mfma_f32_16x16x32_bf16 v[92:95], v[146:149], v[204:207], v[92:95]
	v_mfma_f32_16x16x32_bf16 v[88:91], v[160:163], v[204:207], v[88:91]
	v_mfma_f32_16x16x32_bf16 v[76:79], v[146:149], v[212:215], v[76:79]
	v_mfma_f32_16x16x32_bf16 v[72:75], v[160:163], v[212:215], v[72:75]
	v_mfma_f32_16x16x32_bf16 v[124:127], v[156:159], v[192:195], v[124:127]
	v_mfma_f32_16x16x32_bf16 v[120:123], v[164:167], v[192:195], v[120:123]
	v_mfma_f32_16x16x32_bf16 v[108:111], v[156:159], v[200:203], v[108:111]
	v_mfma_f32_16x16x32_bf16 v[104:107], v[164:167], v[200:203], v[104:107]
	v_mfma_f32_16x16x32_bf16 v[92:95], v[156:159], v[208:211], v[92:95]
	v_mfma_f32_16x16x32_bf16 v[88:91], v[164:167], v[208:211], v[88:91]
	v_mfma_f32_16x16x32_bf16 v[76:79], v[156:159], v[216:219], v[76:79]
	v_mfma_f32_16x16x32_bf16 v[72:75], v[164:167], v[216:219], v[72:75]
	s_setprio 0
	s_setprio 1
	v_mfma_f32_16x16x32_bf16 v[116:119], v[168:171], v[184:187], v[116:119]
	v_mfma_f32_16x16x32_bf16 v[112:115], v[176:179], v[184:187], v[112:115]
	v_mfma_f32_16x16x32_bf16 v[100:103], v[168:171], v[196:199], v[100:103]
	v_mfma_f32_16x16x32_bf16 v[96:99], v[176:179], v[196:199], v[96:99]
	v_mfma_f32_16x16x32_bf16 v[84:87], v[168:171], v[204:207], v[84:87]
	v_mfma_f32_16x16x32_bf16 v[80:83], v[176:179], v[204:207], v[80:83]
	v_mfma_f32_16x16x32_bf16 v[68:71], v[168:171], v[212:215], v[68:71]
	v_mfma_f32_16x16x32_bf16 v[64:67], v[176:179], v[212:215], v[64:67]
	v_mfma_f32_16x16x32_bf16 v[116:119], v[172:175], v[192:195], v[116:119]
	v_mfma_f32_16x16x32_bf16 v[112:115], v[180:183], v[192:195], v[112:115]
	v_mfma_f32_16x16x32_bf16 v[100:103], v[172:175], v[200:203], v[100:103]
	v_mfma_f32_16x16x32_bf16 v[96:99], v[180:183], v[200:203], v[96:99]
	v_mfma_f32_16x16x32_bf16 v[84:87], v[172:175], v[208:211], v[84:87]
	v_mfma_f32_16x16x32_bf16 v[80:83], v[180:183], v[208:211], v[80:83]
	v_mfma_f32_16x16x32_bf16 v[68:71], v[172:175], v[216:219], v[68:71]
	v_mfma_f32_16x16x32_bf16 v[64:67], v[180:183], v[216:219], v[64:67]
	s_setprio 2
	s_barrier
	s_add_i32 s2, s46, s33
	v_lshl_add_u64 v[150:151], v[150:151], 0, s[14:15]
	s_mov_b32 m0, s2
	ds_read_b128 v[184:187], v155 offset:49152
	ds_read_b128 v[192:195], v155 offset:50176
	ds_read_b128 v[196:199], v155 offset:51200
	ds_read_b128 v[200:203], v155 offset:52224
	ds_read_b128 v[204:207], v155 offset:53248
	ds_read_b128 v[208:211], v155 offset:54272
	ds_read_b128 v[212:215], v155 offset:55296
	ds_read_b128 v[216:219], v155 offset:56320
	global_load_lds_dwordx4 v[150:151], off
	s_add_i32 m0, s2, 0x2000
	s_add_u32 s2, s60, 0x80080
	v_lshl_add_u64 v[150:151], v[220:221], 0, s[14:15]
	s_addc_u32 s3, s61, 0
	s_add_i32 s46, s47, s33
	global_load_lds_dwordx4 v[150:151], off
	v_lshl_add_u64 v[150:151], s[2:3], 0, v[130:131]
	s_mov_b32 m0, s46
	s_nop 0
	global_load_lds_dwordx4 v[150:151], off
	v_lshl_add_u64 v[150:151], s[2:3], 0, v[134:135]
	s_add_i32 m0, s46, 0x2000
	s_nop 0
	global_load_lds_dwordx4 v[150:151], off
	v_lshl_add_u64 v[150:151], v[222:223], 0, s[14:15]
	s_mov_b32 m0, s71
	s_nop 0
	global_load_lds_dwordx4 v[150:151], off
	v_lshl_add_u64 v[150:151], v[224:225], 0, s[14:15]
	s_mov_b32 m0, s72
	s_nop 0
	global_load_lds_dwordx4 v[150:151], off
	s_waitcnt vmcnt(8)
	s_waitcnt lgkmcnt(0)
	s_barrier
	s_setprio 1
	s_waitcnt lgkmcnt(0)
	v_mfma_f32_16x16x32_bf16 v[60:63], v[146:149], v[184:187], v[60:63]
	v_mfma_f32_16x16x32_bf16 v[56:59], v[160:163], v[184:187], v[56:59]
	v_mfma_f32_16x16x32_bf16 v[44:47], v[146:149], v[196:199], v[44:47]
	v_mfma_f32_16x16x32_bf16 v[40:43], v[160:163], v[196:199], v[40:43]
	v_mfma_f32_16x16x32_bf16 v[28:31], v[146:149], v[204:207], v[28:31]
	v_mfma_f32_16x16x32_bf16 v[24:27], v[160:163], v[204:207], v[24:27]
	v_mfma_f32_16x16x32_bf16 v[12:15], v[146:149], v[212:215], v[12:15]
	v_mfma_f32_16x16x32_bf16 v[8:11], v[160:163], v[212:215], v[8:11]
	v_mfma_f32_16x16x32_bf16 v[60:63], v[156:159], v[192:195], v[60:63]
	v_mfma_f32_16x16x32_bf16 v[56:59], v[164:167], v[192:195], v[56:59]
	v_mfma_f32_16x16x32_bf16 v[44:47], v[156:159], v[200:203], v[44:47]
	v_mfma_f32_16x16x32_bf16 v[40:43], v[164:167], v[200:203], v[40:43]
	v_mfma_f32_16x16x32_bf16 v[28:31], v[156:159], v[208:211], v[28:31]
	v_mfma_f32_16x16x32_bf16 v[24:27], v[164:167], v[208:211], v[24:27]
	v_mfma_f32_16x16x32_bf16 v[12:15], v[156:159], v[216:219], v[12:15]
	v_mfma_f32_16x16x32_bf16 v[8:11], v[164:167], v[216:219], v[8:11]
	s_setprio 0
	s_setprio 1
	v_mfma_f32_16x16x32_bf16 v[52:55], v[168:171], v[184:187], v[52:55]
	v_mfma_f32_16x16x32_bf16 v[48:51], v[176:179], v[184:187], v[48:51]
	v_mfma_f32_16x16x32_bf16 v[36:39], v[168:171], v[196:199], v[36:39]
	v_mfma_f32_16x16x32_bf16 v[32:35], v[176:179], v[196:199], v[32:35]
	v_mfma_f32_16x16x32_bf16 v[20:23], v[168:171], v[204:207], v[20:23]
	v_mfma_f32_16x16x32_bf16 v[16:19], v[176:179], v[204:207], v[16:19]
	v_mfma_f32_16x16x32_bf16 v[4:7], v[168:171], v[212:215], v[4:7]
	v_mfma_f32_16x16x32_bf16 v[0:3], v[176:179], v[212:215], v[0:3]
	v_mfma_f32_16x16x32_bf16 v[52:55], v[172:175], v[192:195], v[52:55]
	v_mfma_f32_16x16x32_bf16 v[48:51], v[180:183], v[192:195], v[48:51]
	v_mfma_f32_16x16x32_bf16 v[36:39], v[172:175], v[200:203], v[36:39]
	v_mfma_f32_16x16x32_bf16 v[32:35], v[180:183], v[200:203], v[32:35]
	v_mfma_f32_16x16x32_bf16 v[20:23], v[172:175], v[208:211], v[20:23]
	v_mfma_f32_16x16x32_bf16 v[16:19], v[180:183], v[208:211], v[16:19]
	v_mfma_f32_16x16x32_bf16 v[4:7], v[172:175], v[216:219], v[4:7]
	v_mfma_f32_16x16x32_bf16 v[0:3], v[180:183], v[216:219], v[0:3]
	s_setprio 2
	s_barrier
	s_add_i32 s77, s77, 2
	s_add_u32 s56, s56, 0x100
	s_addc_u32 s57, s57, 0
	s_add_u32 s51, s51, 0x100
	s_addc_u32 s76, s76, 0
	s_cmp_gt_u32 s77, 29
	s_cbranch_scc0 .LBB0_497
	s_and_b64 vcc, exec, s[16:17]
	s_cbranch_vccz .LBB0_500
	s_barrier

.LBB0_588:
	ds_read_b128 v[146:149], v154
	ds_read_b128 v[158:161], v154 offset:1024
	ds_read_b128 v[162:165], v154 offset:2048
	ds_read_b128 v[166:169], v154 offset:3072
	ds_read_b128 v[170:173], v155
	ds_read_b128 v[174:177], v155 offset:1024
	ds_read_b128 v[178:181], v155 offset:2048
	ds_read_b128 v[182:185], v155 offset:3072
	s_add_u32 s2, s50, 0xfff80080
	s_addc_u32 s3, s51, -1
	s_cmp_eq_u32 s77, 28
	s_cselect_b32 s61, s7, s3
	s_cselect_b32 s60, s30, s2
	s_cselect_b32 s57, s31, s76
	s_cselect_b32 s56, s37, s39
	v_lshl_add_u64 v[150:151], s[50:51], 0, v[138:139]
	s_add_i32 m0, s34, 0xc000
	ds_read_b128 v[190:193], v156
	ds_read_b128 v[194:197], v156 offset:1024
	ds_read_b128 v[198:201], v156 offset:2048
	ds_read_b128 v[202:205], v156 offset:3072
	ds_read_b128 v[206:209], v156 offset:4096
	ds_read_b128 v[210:213], v156 offset:5120
	ds_read_b128 v[214:217], v156 offset:6144
	ds_read_b128 v[218:221], v156 offset:7168
	global_load_lds_dwordx4 v[150:151], off
	v_lshl_add_u64 v[150:151], s[50:51], 0, v[140:141]
	s_add_i32 m0, s34, 0xe000
	s_nop 0
	global_load_lds_dwordx4 v[150:151], off
	s_waitcnt vmcnt(8)
	s_waitcnt lgkmcnt(0)
	s_barrier
	s_setprio 1
	s_waitcnt lgkmcnt(0)
	v_mfma_f32_16x16x32_bf16 v[124:127], v[146:149], v[190:193], v[124:127]
	v_mfma_f32_16x16x32_bf16 v[120:123], v[162:165], v[190:193], v[120:123]
	v_mfma_f32_16x16x32_bf16 v[108:111], v[146:149], v[198:201], v[108:111]
	v_mfma_f32_16x16x32_bf16 v[104:107], v[162:165], v[198:201], v[104:107]
	v_mfma_f32_16x16x32_bf16 v[92:95], v[146:149], v[206:209], v[92:95]
	v_mfma_f32_16x16x32_bf16 v[88:91], v[162:165], v[206:209], v[88:91]
	v_mfma_f32_16x16x32_bf16 v[76:79], v[146:149], v[214:217], v[76:79]
	v_mfma_f32_16x16x32_bf16 v[72:75], v[162:165], v[214:217], v[72:75]
	v_mfma_f32_16x16x32_bf16 v[124:127], v[158:161], v[194:197], v[124:127]
	v_mfma_f32_16x16x32_bf16 v[120:123], v[166:169], v[194:197], v[120:123]
	v_mfma_f32_16x16x32_bf16 v[108:111], v[158:161], v[202:205], v[108:111]
	v_mfma_f32_16x16x32_bf16 v[104:107], v[166:169], v[202:205], v[104:107]
	v_mfma_f32_16x16x32_bf16 v[92:95], v[158:161], v[210:213], v[92:95]
	v_mfma_f32_16x16x32_bf16 v[88:91], v[166:169], v[210:213], v[88:91]
	v_mfma_f32_16x16x32_bf16 v[76:79], v[158:161], v[218:221], v[76:79]
	v_mfma_f32_16x16x32_bf16 v[72:75], v[166:169], v[218:221], v[72:75]
	s_setprio 0
	s_setprio 1
	v_mfma_f32_16x16x32_bf16 v[116:119], v[170:173], v[190:193], v[116:119]
	v_mfma_f32_16x16x32_bf16 v[112:115], v[178:181], v[190:193], v[112:115]
	v_mfma_f32_16x16x32_bf16 v[100:103], v[170:173], v[198:201], v[100:103]
	v_mfma_f32_16x16x32_bf16 v[96:99], v[178:181], v[198:201], v[96:99]
	v_mfma_f32_16x16x32_bf16 v[84:87], v[170:173], v[206:209], v[84:87]
	v_mfma_f32_16x16x32_bf16 v[80:83], v[178:181], v[206:209], v[80:83]
	v_mfma_f32_16x16x32_bf16 v[68:71], v[170:173], v[214:217], v[68:71]
	v_mfma_f32_16x16x32_bf16 v[64:67], v[178:181], v[214:217], v[64:67]
	v_mfma_f32_16x16x32_bf16 v[116:119], v[174:177], v[194:197], v[116:119]
	v_mfma_f32_16x16x32_bf16 v[112:115], v[182:185], v[194:197], v[112:115]
	v_mfma_f32_16x16x32_bf16 v[100:103], v[174:177], v[202:205], v[100:103]
	v_mfma_f32_16x16x32_bf16 v[96:99], v[182:185], v[202:205], v[96:99]
	v_mfma_f32_16x16x32_bf16 v[84:87], v[174:177], v[210:213], v[84:87]
	v_mfma_f32_16x16x32_bf16 v[80:83], v[182:185], v[210:213], v[80:83]
	v_mfma_f32_16x16x32_bf16 v[68:71], v[174:177], v[218:221], v[68:71]
	v_mfma_f32_16x16x32_bf16 v[64:67], v[182:185], v[218:221], v[64:67]
	s_setprio 2
	s_barrier
	s_add_i32 s2, s69, s33
	v_lshl_add_u64 v[150:151], s[56:57], 0, v[130:131]
	s_mov_b32 m0, s2
	ds_read_b128 v[190:193], v156 offset:16384
	ds_read_b128 v[194:197], v156 offset:17408
	ds_read_b128 v[198:201], v156 offset:18432
	ds_read_b128 v[202:205], v156 offset:19456
	ds_read_b128 v[206:209], v156 offset:20480
	ds_read_b128 v[210:213], v156 offset:21504
	ds_read_b128 v[214:217], v156 offset:22528
	ds_read_b128 v[218:221], v156 offset:23552
	global_load_lds_dwordx4 v[150:151], off
	s_add_i32 m0, s2, 0x2000
	s_add_u32 s2, s56, 0x80000
	v_lshl_add_u64 v[186:187], s[56:57], 0, v[134:135]
	s_addc_u32 s3, s57, 0
	s_add_i32 s46, s70, s33
	global_load_lds_dwordx4 v[186:187], off
	v_lshl_add_u64 v[222:223], s[2:3], 0, v[130:131]
	s_mov_b32 m0, s46
	v_lshl_add_u64 v[224:225], s[60:61], 0, v[132:133]
	global_load_lds_dwordx4 v[222:223], off
	v_lshl_add_u64 v[222:223], s[2:3], 0, v[134:135]
	s_add_i32 m0, s46, 0x2000
	s_nop 0
	global_load_lds_dwordx4 v[222:223], off
	v_lshl_add_u64 v[222:223], s[60:61], 0, v[128:129]
	s_mov_b32 m0, s34
	s_nop 0
	global_load_lds_dwordx4 v[222:223], off
	s_mov_b32 m0, s35
	s_nop 0
	global_load_lds_dwordx4 v[224:225], off
	s_waitcnt vmcnt(8)
	s_waitcnt lgkmcnt(0)
	s_barrier
	s_setprio 1
	s_waitcnt lgkmcnt(0)
	v_mfma_f32_16x16x32_bf16 v[60:63], v[146:149], v[190:193], v[60:63]
	v_mfma_f32_16x16x32_bf16 v[56:59], v[162:165], v[190:193], v[56:59]
	v_mfma_f32_16x16x32_bf16 v[44:47], v[146:149], v[198:201], v[44:47]
	v_mfma_f32_16x16x32_bf16 v[40:43], v[162:165], v[198:201], v[40:43]
	v_mfma_f32_16x16x32_bf16 v[28:31], v[146:149], v[206:209], v[28:31]
	v_mfma_f32_16x16x32_bf16 v[24:27], v[162:165], v[206:209], v[24:27]
	v_mfma_f32_16x16x32_bf16 v[12:15], v[146:149], v[214:217], v[12:15]
	v_mfma_f32_16x16x32_bf16 v[8:11], v[162:165], v[214:217], v[8:11]
	v_mfma_f32_16x16x32_bf16 v[60:63], v[158:161], v[194:197], v[60:63]
	v_mfma_f32_16x16x32_bf16 v[56:59], v[166:169], v[194:197], v[56:59]
	v_mfma_f32_16x16x32_bf16 v[44:47], v[158:161], v[202:205], v[44:47]
	v_mfma_f32_16x16x32_bf16 v[40:43], v[166:169], v[202:205], v[40:43]
	v_mfma_f32_16x16x32_bf16 v[28:31], v[158:161], v[210:213], v[28:31]
	v_mfma_f32_16x16x32_bf16 v[24:27], v[166:169], v[210:213], v[24:27]
	v_mfma_f32_16x16x32_bf16 v[12:15], v[158:161], v[218:221], v[12:15]
	v_mfma_f32_16x16x32_bf16 v[8:11], v[166:169], v[218:221], v[8:11]
	s_setprio 0
	s_setprio 1
	v_mfma_f32_16x16x32_bf16 v[52:55], v[170:173], v[190:193], v[52:55]
	v_mfma_f32_16x16x32_bf16 v[48:51], v[178:181], v[190:193], v[48:51]
	v_mfma_f32_16x16x32_bf16 v[36:39], v[170:173], v[198:201], v[36:39]
	v_mfma_f32_16x16x32_bf16 v[32:35], v[178:181], v[198:201], v[32:35]
	v_mfma_f32_16x16x32_bf16 v[20:23], v[170:173], v[206:209], v[20:23]
	v_mfma_f32_16x16x32_bf16 v[16:19], v[178:181], v[206:209], v[16:19]
	v_mfma_f32_16x16x32_bf16 v[4:7], v[170:173], v[214:217], v[4:7]
	v_mfma_f32_16x16x32_bf16 v[0:3], v[178:181], v[214:217], v[0:3]
	v_mfma_f32_16x16x32_bf16 v[52:55], v[174:177], v[194:197], v[52:55]
	v_mfma_f32_16x16x32_bf16 v[48:51], v[182:185], v[194:197], v[48:51]
	v_mfma_f32_16x16x32_bf16 v[36:39], v[174:177], v[202:205], v[36:39]
	v_mfma_f32_16x16x32_bf16 v[32:35], v[182:185], v[202:205], v[32:35]
	v_mfma_f32_16x16x32_bf16 v[20:23], v[174:177], v[210:213], v[20:23]
	v_mfma_f32_16x16x32_bf16 v[16:19], v[182:185], v[210:213], v[16:19]
	v_mfma_f32_16x16x32_bf16 v[4:7], v[174:177], v[218:221], v[4:7]
	v_mfma_f32_16x16x32_bf16 v[0:3], v[182:185], v[218:221], v[0:3]
	s_setprio 2
	s_barrier
	s_add_i32 s46, 0, 0x18000
	s_add_i32 s47, 0, 0x1c000
	v_add_u32_e32 v166, s46, v153
	v_add_u32_e32 v182, s47, v153
	ds_read_b128 v[146:149], v166
	ds_read_b128 v[158:161], v166 offset:1024
	ds_read_b128 v[162:165], v166 offset:2048
	ds_read_b128 v[166:169], v166 offset:3072
	ds_read_b128 v[170:173], v182
	ds_read_b128 v[174:177], v182 offset:1024
	ds_read_b128 v[178:181], v182 offset:2048
	ds_read_b128 v[182:185], v182 offset:3072
	s_add_u32 s2, s60, 0x80000
	s_addc_u32 s3, s61, 0
	s_mov_b32 m0, s64
	v_lshl_add_u64 v[226:227], s[2:3], 0, v[128:129]
	ds_read_b128 v[190:193], v156 offset:32768
	ds_read_b128 v[194:197], v156 offset:33792
	ds_read_b128 v[198:201], v156 offset:34816
	ds_read_b128 v[202:205], v156 offset:35840
	ds_read_b128 v[206:209], v156 offset:36864
	ds_read_b128 v[210:213], v156 offset:37888
	ds_read_b128 v[214:217], v156 offset:38912
	ds_read_b128 v[218:221], v156 offset:39936
	global_load_lds_dwordx4 v[226:227], off
	v_lshl_add_u64 v[226:227], s[2:3], 0, v[132:133]
	s_mov_b32 m0, s65
	s_nop 0
	global_load_lds_dwordx4 v[226:227], off
	s_waitcnt vmcnt(8)
	s_waitcnt lgkmcnt(0)
	s_barrier
	s_setprio 1
	s_waitcnt lgkmcnt(0)
	v_mfma_f32_16x16x32_bf16 v[124:127], v[146:149], v[190:193], v[124:127]
	v_mfma_f32_16x16x32_bf16 v[120:123], v[162:165], v[190:193], v[120:123]
	v_mfma_f32_16x16x32_bf16 v[108:111], v[146:149], v[198:201], v[108:111]
	v_mfma_f32_16x16x32_bf16 v[104:107], v[162:165], v[198:201], v[104:107]
	v_mfma_f32_16x16x32_bf16 v[92:95], v[146:149], v[206:209], v[92:95]
	v_mfma_f32_16x16x32_bf16 v[88:91], v[162:165], v[206:209], v[88:91]
	v_mfma_f32_16x16x32_bf16 v[76:79], v[146:149], v[214:217], v[76:79]
	v_mfma_f32_16x16x32_bf16 v[72:75], v[162:165], v[214:217], v[72:75]
	v_mfma_f32_16x16x32_bf16 v[124:127], v[158:161], v[194:197], v[124:127]
	v_mfma_f32_16x16x32_bf16 v[120:123], v[166:169], v[194:197], v[120:123]
	v_mfma_f32_16x16x32_bf16 v[108:111], v[158:161], v[202:205], v[108:111]
	v_mfma_f32_16x16x32_bf16 v[104:107], v[166:169], v[202:205], v[104:107]
	v_mfma_f32_16x16x32_bf16 v[92:95], v[158:161], v[210:213], v[92:95]
	v_mfma_f32_16x16x32_bf16 v[88:91], v[166:169], v[210:213], v[88:91]
	v_mfma_f32_16x16x32_bf16 v[76:79], v[158:161], v[218:221], v[76:79]
	v_mfma_f32_16x16x32_bf16 v[72:75], v[166:169], v[218:221], v[72:75]
	s_setprio 0
	s_setprio 1
	v_mfma_f32_16x16x32_bf16 v[116:119], v[170:173], v[190:193], v[116:119]
	v_mfma_f32_16x16x32_bf16 v[112:115], v[178:181], v[190:193], v[112:115]
	v_mfma_f32_16x16x32_bf16 v[100:103], v[170:173], v[198:201], v[100:103]
	v_mfma_f32_16x16x32_bf16 v[96:99], v[178:181], v[198:201], v[96:99]
	v_mfma_f32_16x16x32_bf16 v[84:87], v[170:173], v[206:209], v[84:87]
	v_mfma_f32_16x16x32_bf16 v[80:83], v[178:181], v[206:209], v[80:83]
	v_mfma_f32_16x16x32_bf16 v[68:71], v[170:173], v[214:217], v[68:71]
	v_mfma_f32_16x16x32_bf16 v[64:67], v[178:181], v[214:217], v[64:67]
	v_mfma_f32_16x16x32_bf16 v[116:119], v[174:177], v[194:197], v[116:119]
	v_mfma_f32_16x16x32_bf16 v[112:115], v[182:185], v[194:197], v[112:115]
	v_mfma_f32_16x16x32_bf16 v[100:103], v[174:177], v[202:205], v[100:103]
	v_mfma_f32_16x16x32_bf16 v[96:99], v[182:185], v[202:205], v[96:99]
	v_mfma_f32_16x16x32_bf16 v[84:87], v[174:177], v[210:213], v[84:87]
	v_mfma_f32_16x16x32_bf16 v[80:83], v[182:185], v[210:213], v[80:83]
	v_mfma_f32_16x16x32_bf16 v[68:71], v[174:177], v[218:221], v[68:71]
	v_mfma_f32_16x16x32_bf16 v[64:67], v[182:185], v[218:221], v[64:67]
	s_setprio 2
	s_barrier
	s_add_i32 s2, s46, s33
	v_lshl_add_u64 v[150:151], v[150:151], 0, s[14:15]
	s_mov_b32 m0, s2
	ds_read_b128 v[190:193], v156 offset:49152
	ds_read_b128 v[194:197], v156 offset:50176
	ds_read_b128 v[198:201], v156 offset:51200
	ds_read_b128 v[202:205], v156 offset:52224
	ds_read_b128 v[206:209], v156 offset:53248
	ds_read_b128 v[210:213], v156 offset:54272
	ds_read_b128 v[214:217], v156 offset:55296
	ds_read_b128 v[218:221], v156 offset:56320
	global_load_lds_dwordx4 v[150:151], off
	s_add_i32 m0, s2, 0x2000
	s_add_u32 s2, s56, 0x80080
	v_lshl_add_u64 v[150:151], v[186:187], 0, s[14:15]
	s_addc_u32 s3, s57, 0
	s_add_i32 s46, s47, s33
	global_load_lds_dwordx4 v[150:151], off
	v_lshl_add_u64 v[150:151], s[2:3], 0, v[130:131]
	s_mov_b32 m0, s46
	s_nop 0
	global_load_lds_dwordx4 v[150:151], off
	v_lshl_add_u64 v[150:151], s[2:3], 0, v[134:135]
	s_add_i32 m0, s46, 0x2000
	s_nop 0
	global_load_lds_dwordx4 v[150:151], off
	v_lshl_add_u64 v[150:151], v[222:223], 0, s[14:15]
	s_mov_b32 m0, s67
	s_nop 0
	global_load_lds_dwordx4 v[150:151], off
	v_lshl_add_u64 v[150:151], v[224:225], 0, s[14:15]
	s_mov_b32 m0, s68
	s_nop 0
	global_load_lds_dwordx4 v[150:151], off
	s_waitcnt vmcnt(8)
	s_waitcnt lgkmcnt(0)
	s_barrier
	s_setprio 1
	s_waitcnt lgkmcnt(0)
	v_mfma_f32_16x16x32_bf16 v[60:63], v[146:149], v[190:193], v[60:63]
	v_mfma_f32_16x16x32_bf16 v[56:59], v[162:165], v[190:193], v[56:59]
	v_mfma_f32_16x16x32_bf16 v[44:47], v[146:149], v[198:201], v[44:47]
	v_mfma_f32_16x16x32_bf16 v[40:43], v[162:165], v[198:201], v[40:43]
	v_mfma_f32_16x16x32_bf16 v[28:31], v[146:149], v[206:209], v[28:31]
	v_mfma_f32_16x16x32_bf16 v[24:27], v[162:165], v[206:209], v[24:27]
	v_mfma_f32_16x16x32_bf16 v[12:15], v[146:149], v[214:217], v[12:15]
	v_mfma_f32_16x16x32_bf16 v[8:11], v[162:165], v[214:217], v[8:11]
	v_mfma_f32_16x16x32_bf16 v[60:63], v[158:161], v[194:197], v[60:63]
	v_mfma_f32_16x16x32_bf16 v[56:59], v[166:169], v[194:197], v[56:59]
	v_mfma_f32_16x16x32_bf16 v[44:47], v[158:161], v[202:205], v[44:47]
	v_mfma_f32_16x16x32_bf16 v[40:43], v[166:169], v[202:205], v[40:43]
	v_mfma_f32_16x16x32_bf16 v[28:31], v[158:161], v[210:213], v[28:31]
	v_mfma_f32_16x16x32_bf16 v[24:27], v[166:169], v[210:213], v[24:27]
	v_mfma_f32_16x16x32_bf16 v[12:15], v[158:161], v[218:221], v[12:15]
	v_mfma_f32_16x16x32_bf16 v[8:11], v[166:169], v[218:221], v[8:11]
	s_setprio 0
	s_setprio 1
	v_mfma_f32_16x16x32_bf16 v[52:55], v[170:173], v[190:193], v[52:55]
	v_mfma_f32_16x16x32_bf16 v[48:51], v[178:181], v[190:193], v[48:51]
	v_mfma_f32_16x16x32_bf16 v[36:39], v[170:173], v[198:201], v[36:39]
	v_mfma_f32_16x16x32_bf16 v[32:35], v[178:181], v[198:201], v[32:35]
	v_mfma_f32_16x16x32_bf16 v[20:23], v[170:173], v[206:209], v[20:23]
	v_mfma_f32_16x16x32_bf16 v[16:19], v[178:181], v[206:209], v[16:19]
	v_mfma_f32_16x16x32_bf16 v[4:7], v[170:173], v[214:217], v[4:7]
	v_mfma_f32_16x16x32_bf16 v[0:3], v[178:181], v[214:217], v[0:3]
	v_mfma_f32_16x16x32_bf16 v[52:55], v[174:177], v[194:197], v[52:55]
	v_mfma_f32_16x16x32_bf16 v[48:51], v[182:185], v[194:197], v[48:51]
	v_mfma_f32_16x16x32_bf16 v[36:39], v[174:177], v[202:205], v[36:39]
	v_mfma_f32_16x16x32_bf16 v[32:35], v[182:185], v[202:205], v[32:35]
	v_mfma_f32_16x16x32_bf16 v[20:23], v[174:177], v[210:213], v[20:23]
	v_mfma_f32_16x16x32_bf16 v[16:19], v[182:185], v[210:213], v[16:19]
	v_mfma_f32_16x16x32_bf16 v[4:7], v[174:177], v[218:221], v[4:7]
	v_mfma_f32_16x16x32_bf16 v[0:3], v[182:185], v[218:221], v[0:3]
	s_setprio 2
	s_barrier
	s_add_i32 s77, s77, 2
	s_add_u32 s50, s50, 0x100
	s_addc_u32 s51, s51, 0
	s_add_u32 s39, s39, 0x100
	s_addc_u32 s76, s76, 0
	s_cmp_gt_u32 s77, 29
	s_cbranch_scc0 .LBB0_588
	s_and_b64 vcc, exec, s[16:17]
	s_cbranch_vccz .LBB0_591
	s_barrier

.LBB0_883:
	ds_read_b128 v[146:149], v153
	ds_read_b128 v[156:159], v153 offset:1024
	ds_read_b128 v[160:163], v153 offset:2048
	ds_read_b128 v[164:167], v153 offset:3072
	ds_read_b128 v[168:171], v154
	ds_read_b128 v[172:175], v154 offset:1024
	ds_read_b128 v[176:179], v154 offset:2048
	ds_read_b128 v[180:183], v154 offset:3072
	s_add_u32 s2, s38, 0xfff80080
	s_addc_u32 s3, s39, -1
	s_cmp_eq_u32 s61, 28
	s_cselect_b32 s43, s21, s3
	s_cselect_b32 s42, s25, s2
	s_cselect_b32 s41, s57, s60
	s_cselect_b32 s40, s58, s59
	v_lshl_add_u64 v[150:151], s[38:39], 0, v[138:139]
	s_add_i32 m0, s37, 0xc000
	ds_read_b128 v[184:187], v155
	ds_read_b128 v[188:191], v155 offset:1024
	ds_read_b128 v[192:195], v155 offset:2048
	ds_read_b128 v[196:199], v155 offset:3072
	ds_read_b128 v[200:203], v155 offset:4096
	ds_read_b128 v[204:207], v155 offset:5120
	ds_read_b128 v[208:211], v155 offset:6144
	ds_read_b128 v[212:215], v155 offset:7168
	global_load_lds_dwordx4 v[150:151], off
	v_lshl_add_u64 v[150:151], s[38:39], 0, v[140:141]
	s_add_i32 m0, s37, 0xe000
	s_nop 0
	global_load_lds_dwordx4 v[150:151], off
	s_waitcnt vmcnt(8)
	s_waitcnt lgkmcnt(0)
	s_barrier
	s_setprio 1
	s_waitcnt lgkmcnt(0)
	v_mfma_f32_16x16x32_bf16 v[124:127], v[146:149], v[184:187], v[124:127]
	v_mfma_f32_16x16x32_bf16 v[120:123], v[160:163], v[184:187], v[120:123]
	v_mfma_f32_16x16x32_bf16 v[108:111], v[146:149], v[192:195], v[108:111]
	v_mfma_f32_16x16x32_bf16 v[104:107], v[160:163], v[192:195], v[104:107]
	v_mfma_f32_16x16x32_bf16 v[92:95], v[146:149], v[200:203], v[92:95]
	v_mfma_f32_16x16x32_bf16 v[88:91], v[160:163], v[200:203], v[88:91]
	v_mfma_f32_16x16x32_bf16 v[76:79], v[146:149], v[208:211], v[76:79]
	v_mfma_f32_16x16x32_bf16 v[72:75], v[160:163], v[208:211], v[72:75]
	v_mfma_f32_16x16x32_bf16 v[124:127], v[156:159], v[188:191], v[124:127]
	v_mfma_f32_16x16x32_bf16 v[120:123], v[164:167], v[188:191], v[120:123]
	v_mfma_f32_16x16x32_bf16 v[108:111], v[156:159], v[196:199], v[108:111]
	v_mfma_f32_16x16x32_bf16 v[104:107], v[164:167], v[196:199], v[104:107]
	v_mfma_f32_16x16x32_bf16 v[92:95], v[156:159], v[204:207], v[92:95]
	v_mfma_f32_16x16x32_bf16 v[88:91], v[164:167], v[204:207], v[88:91]
	v_mfma_f32_16x16x32_bf16 v[76:79], v[156:159], v[212:215], v[76:79]
	v_mfma_f32_16x16x32_bf16 v[72:75], v[164:167], v[212:215], v[72:75]
	s_setprio 0
	s_setprio 1
	v_mfma_f32_16x16x32_bf16 v[116:119], v[168:171], v[184:187], v[116:119]
	v_mfma_f32_16x16x32_bf16 v[112:115], v[176:179], v[184:187], v[112:115]
	v_mfma_f32_16x16x32_bf16 v[100:103], v[168:171], v[192:195], v[100:103]
	v_mfma_f32_16x16x32_bf16 v[96:99], v[176:179], v[192:195], v[96:99]
	v_mfma_f32_16x16x32_bf16 v[84:87], v[168:171], v[200:203], v[84:87]
	v_mfma_f32_16x16x32_bf16 v[80:83], v[176:179], v[200:203], v[80:83]
	v_mfma_f32_16x16x32_bf16 v[68:71], v[168:171], v[208:211], v[68:71]
	v_mfma_f32_16x16x32_bf16 v[64:67], v[176:179], v[208:211], v[64:67]
	v_mfma_f32_16x16x32_bf16 v[116:119], v[172:175], v[188:191], v[116:119]
	v_mfma_f32_16x16x32_bf16 v[112:115], v[180:183], v[188:191], v[112:115]
	v_mfma_f32_16x16x32_bf16 v[100:103], v[172:175], v[196:199], v[100:103]
	v_mfma_f32_16x16x32_bf16 v[96:99], v[180:183], v[196:199], v[96:99]
	v_mfma_f32_16x16x32_bf16 v[84:87], v[172:175], v[204:207], v[84:87]
	v_mfma_f32_16x16x32_bf16 v[80:83], v[180:183], v[204:207], v[80:83]
	v_mfma_f32_16x16x32_bf16 v[68:71], v[172:175], v[212:215], v[68:71]
	v_mfma_f32_16x16x32_bf16 v[64:67], v[180:183], v[212:215], v[64:67]
	s_setprio 2
	s_barrier
	s_add_i32 s2, s54, s47
	v_lshl_add_u64 v[150:151], s[40:41], 0, v[132:133]
	s_mov_b32 m0, s2
	ds_read_b128 v[184:187], v155 offset:16384
	ds_read_b128 v[188:191], v155 offset:17408
	ds_read_b128 v[192:195], v155 offset:18432
	ds_read_b128 v[196:199], v155 offset:19456
	ds_read_b128 v[200:203], v155 offset:20480
	ds_read_b128 v[204:207], v155 offset:21504
	ds_read_b128 v[208:211], v155 offset:22528
	ds_read_b128 v[212:215], v155 offset:23552
	global_load_lds_dwordx4 v[150:151], off
	s_add_i32 m0, s2, 0x2000
	s_add_u32 s2, s40, 0x80000
	v_lshl_add_u64 v[216:217], s[40:41], 0, v[128:129]
	s_addc_u32 s3, s41, 0
	s_add_i32 s22, s55, s47
	global_load_lds_dwordx4 v[216:217], off
	v_lshl_add_u64 v[218:219], s[2:3], 0, v[132:133]
	s_mov_b32 m0, s22
	v_lshl_add_u64 v[220:221], s[42:43], 0, v[130:131]
	global_load_lds_dwordx4 v[218:219], off
	v_lshl_add_u64 v[218:219], s[2:3], 0, v[128:129]
	s_add_i32 m0, s22, 0x2000
	s_nop 0
	global_load_lds_dwordx4 v[218:219], off
	v_lshl_add_u64 v[218:219], s[42:43], 0, v[134:135]
	s_mov_b32 m0, s37
	s_nop 0
	global_load_lds_dwordx4 v[218:219], off
	s_mov_b32 m0, s48
	s_nop 0
	global_load_lds_dwordx4 v[220:221], off
	s_waitcnt vmcnt(8)
	s_waitcnt lgkmcnt(0)
	s_barrier
; #define PG8_STAGE(bufoff, gbase, voff) do { _Pragma("unroll") for (int _i = 0; _i < 2; ++_i) \
;         __builtin_amdgcn_global_load_lds((const unsigned*)((const char*)(gbase) + (voff)[_i]), (LAS unsigned*)(lds + (bufoff) + ldsw + _i * 8192), 16, 0, 0); } while (0)
; #define PG8_LDA(dst, b, h) do { _Pragma("unroll") for (int m = 0; m < 4; ++m) _Pragma("unroll") for (int k = 0; k < 2; ++k) dst[m][k] = *(const LAS bf16x8*)(lds + PG8_SA(b, h) + aoff + m * 2048 + k * 1024); } while (0)
; #define PG8_LDB(dst, b, h) do { _Pragma("unroll") for (int n = 0; n < 2; ++n) _Pragma("unroll") for (int k = 0; k < 2; ++k) dst[n][k] = *(const LAS bf16x8*)(lds + PG8_SB(b, h) + boff + n * 2048 + k * 1024); } while (0)
; #define PG8_MMA(ai, bj, At, Bt) do { __builtin_amdgcn_s_setprio(1); _Pragma("unroll") for (int m = 0; m < 4; ++m) _Pragma("unroll") for (int n = 0; n < 2; ++n) _Pragma("unroll") for (int k = 0; k < 2; ++k) \
;         acc[ai][bj][m][n] = __builtin_amdgcn_mfma_f32_16x16x32_bf16(Bt[n][k], At[m][k], acc[ai][bj][m][n], 0, 0, 0); __builtin_amdgcn_s_setprio(0); } while (0)
; #define PG8_WAIT_V(n) asm volatile("s_waitcnt vmcnt(" #n ")" ::: "memory")
; #define PG8_WAIT_L(n) asm volatile("s_waitcnt lgkmcnt(" #n ")" ::: "memory")
; #define PG8_BAR __builtin_amdgcn_s_barrier()
; #define PG8_SCHED __builtin_amdgcn_sched_barrier(0)
; template <class Epi, class Sched>
; __device__ __forceinline__ void gemm_phase(LAS unsigned char* lds, const Gemm g, const Sched& S, const Epi& E) {
;     ...
;             PG8_WAIT_V(8); PG8_WAIT_L(0); PG8_BAR; PG8_MMA(1, 0, At, B0); PG8_MMA(1, 1, At, B1); PG8_BAR; PG8_SCHED;
;             PG8_LDB(B0, 1, 0); PG8_LDB(B1, 1, 1); PG8_SCHED; PG8_LDA(At, 1, 0); PG8_STAGE(PG8_SA(0, 1), a2 + hstepA, voffA);
;             PG8_WAIT_V(8); PG8_WAIT_L(0); PG8_BAR; PG8_MMA(0, 0, At, B0); PG8_MMA(0, 1, At, B1); PG8_BAR; PG8_SCHED;
	s_setprio 1
	s_waitcnt lgkmcnt(0)
	v_mfma_f32_16x16x32_bf16 v[60:63], v[146:149], v[184:187], v[60:63]
	v_mfma_f32_16x16x32_bf16 v[56:59], v[160:163], v[184:187], v[56:59]
	v_mfma_f32_16x16x32_bf16 v[44:47], v[146:149], v[192:195], v[44:47]
	v_mfma_f32_16x16x32_bf16 v[40:43], v[160:163], v[192:195], v[40:43]
	v_mfma_f32_16x16x32_bf16 v[28:31], v[146:149], v[200:203], v[28:31]
	v_mfma_f32_16x16x32_bf16 v[24:27], v[160:163], v[200:203], v[24:27]
	v_mfma_f32_16x16x32_bf16 v[12:15], v[146:149], v[208:211], v[12:15]
	v_mfma_f32_16x16x32_bf16 v[8:11], v[160:163], v[208:211], v[8:11]
	v_mfma_f32_16x16x32_bf16 v[60:63], v[156:159], v[188:191], v[60:63]
	v_mfma_f32_16x16x32_bf16 v[56:59], v[164:167], v[188:191], v[56:59]
	v_mfma_f32_16x16x32_bf16 v[44:47], v[156:159], v[196:199], v[44:47]
	v_mfma_f32_16x16x32_bf16 v[40:43], v[164:167], v[196:199], v[40:43]
	v_mfma_f32_16x16x32_bf16 v[28:31], v[156:159], v[204:207], v[28:31]
	v_mfma_f32_16x16x32_bf16 v[24:27], v[164:167], v[204:207], v[24:27]
	v_mfma_f32_16x16x32_bf16 v[12:15], v[156:159], v[212:215], v[12:15]
	v_mfma_f32_16x16x32_bf16 v[8:11], v[164:167], v[212:215], v[8:11]
	s_setprio 0
	s_setprio 1
	v_mfma_f32_16x16x32_bf16 v[52:55], v[168:171], v[184:187], v[52:55]
	v_mfma_f32_16x16x32_bf16 v[48:51], v[176:179], v[184:187], v[48:51]
	v_mfma_f32_16x16x32_bf16 v[36:39], v[168:171], v[192:195], v[36:39]
	v_mfma_f32_16x16x32_bf16 v[32:35], v[176:179], v[192:195], v[32:35]
	v_mfma_f32_16x16x32_bf16 v[20:23], v[168:171], v[200:203], v[20:23]
	v_mfma_f32_16x16x32_bf16 v[16:19], v[176:179], v[200:203], v[16:19]
	v_mfma_f32_16x16x32_bf16 v[4:7], v[168:171], v[208:211], v[4:7]
	v_mfma_f32_16x16x32_bf16 v[0:3], v[176:179], v[208:211], v[0:3]
	v_mfma_f32_16x16x32_bf16 v[52:55], v[172:175], v[188:191], v[52:55]
	v_mfma_f32_16x16x32_bf16 v[48:51], v[180:183], v[188:191], v[48:51]
	v_mfma_f32_16x16x32_bf16 v[36:39], v[172:175], v[196:199], v[36:39]
	v_mfma_f32_16x16x32_bf16 v[32:35], v[180:183], v[196:199], v[32:35]
	v_mfma_f32_16x16x32_bf16 v[20:23], v[172:175], v[204:207], v[20:23]
	v_mfma_f32_16x16x32_bf16 v[16:19], v[180:183], v[204:207], v[16:19]
	v_mfma_f32_16x16x32_bf16 v[4:7], v[172:175], v[212:215], v[4:7]
	v_mfma_f32_16x16x32_bf16 v[0:3], v[180:183], v[212:215], v[0:3]
	s_setprio 2
	s_barrier
	s_add_i32 s22, 0, 0x18000
	s_add_i32 s23, 0, 0x1c000
	v_add_u32_e32 v164, s22, v152
	v_add_u32_e32 v180, s23, v152
	ds_read_b128 v[146:149], v164
	ds_read_b128 v[156:159], v164 offset:1024
	ds_read_b128 v[160:163], v164 offset:2048
	ds_read_b128 v[164:167], v164 offset:3072
	ds_read_b128 v[168:171], v180
	ds_read_b128 v[172:175], v180 offset:1024
	ds_read_b128 v[176:179], v180 offset:2048
	ds_read_b128 v[180:183], v180 offset:3072
	s_add_u32 s2, s42, 0x80000
	s_addc_u32 s3, s43, 0
	s_mov_b32 m0, s49
	v_lshl_add_u64 v[222:223], s[2:3], 0, v[134:135]
	ds_read_b128 v[184:187], v155 offset:32768
	ds_read_b128 v[188:191], v155 offset:33792
	ds_read_b128 v[192:195], v155 offset:34816
	ds_read_b128 v[196:199], v155 offset:35840
	ds_read_b128 v[200:203], v155 offset:36864
	ds_read_b128 v[204:207], v155 offset:37888
	ds_read_b128 v[208:211], v155 offset:38912
	ds_read_b128 v[212:215], v155 offset:39936
	global_load_lds_dwordx4 v[222:223], off
	v_lshl_add_u64 v[222:223], s[2:3], 0, v[130:131]
	s_mov_b32 m0, s50
	s_nop 0
	global_load_lds_dwordx4 v[222:223], off
	s_waitcnt vmcnt(8)
	s_waitcnt lgkmcnt(0)
	s_barrier
	s_setprio 1
	s_waitcnt lgkmcnt(0)
	v_mfma_f32_16x16x32_bf16 v[124:127], v[146:149], v[184:187], v[124:127]
	v_mfma_f32_16x16x32_bf16 v[120:123], v[160:163], v[184:187], v[120:123]
	v_mfma_f32_16x16x32_bf16 v[108:111], v[146:149], v[192:195], v[108:111]
	v_mfma_f32_16x16x32_bf16 v[104:107], v[160:163], v[192:195], v[104:107]
	v_mfma_f32_16x16x32_bf16 v[92:95], v[146:149], v[200:203], v[92:95]
	v_mfma_f32_16x16x32_bf16 v[88:91], v[160:163], v[200:203], v[88:91]
	v_mfma_f32_16x16x32_bf16 v[76:79], v[146:149], v[208:211], v[76:79]
	v_mfma_f32_16x16x32_bf16 v[72:75], v[160:163], v[208:211], v[72:75]
	v_mfma_f32_16x16x32_bf16 v[124:127], v[156:159], v[188:191], v[124:127]
	v_mfma_f32_16x16x32_bf16 v[120:123], v[164:167], v[188:191], v[120:123]
	v_mfma_f32_16x16x32_bf16 v[108:111], v[156:159], v[196:199], v[108:111]
	v_mfma_f32_16x16x32_bf16 v[104:107], v[164:167], v[196:199], v[104:107]
	v_mfma_f32_16x16x32_bf16 v[92:95], v[156:159], v[204:207], v[92:95]
	v_mfma_f32_16x16x32_bf16 v[88:91], v[164:167], v[204:207], v[88:91]
	v_mfma_f32_16x16x32_bf16 v[76:79], v[156:159], v[212:215], v[76:79]
	v_mfma_f32_16x16x32_bf16 v[72:75], v[164:167], v[212:215], v[72:75]
	s_setprio 0
	s_setprio 1
	v_mfma_f32_16x16x32_bf16 v[116:119], v[168:171], v[184:187], v[116:119]
	v_mfma_f32_16x16x32_bf16 v[112:115], v[176:179], v[184:187], v[112:115]
	v_mfma_f32_16x16x32_bf16 v[100:103], v[168:171], v[192:195], v[100:103]
	v_mfma_f32_16x16x32_bf16 v[96:99], v[176:179], v[192:195], v[96:99]
	v_mfma_f32_16x16x32_bf16 v[84:87], v[168:171], v[200:203], v[84:87]
	v_mfma_f32_16x16x32_bf16 v[80:83], v[176:179], v[200:203], v[80:83]
	v_mfma_f32_16x16x32_bf16 v[68:71], v[168:171], v[208:211], v[68:71]
	v_mfma_f32_16x16x32_bf16 v[64:67], v[176:179], v[208:211], v[64:67]
	v_mfma_f32_16x16x32_bf16 v[116:119], v[172:175], v[188:191], v[116:119]
	v_mfma_f32_16x16x32_bf16 v[112:115], v[180:183], v[188:191], v[112:115]
	v_mfma_f32_16x16x32_bf16 v[100:103], v[172:175], v[196:199], v[100:103]
	v_mfma_f32_16x16x32_bf16 v[96:99], v[180:183], v[196:199], v[96:99]
	v_mfma_f32_16x16x32_bf16 v[84:87], v[172:175], v[204:207], v[84:87]
	v_mfma_f32_16x16x32_bf16 v[80:83], v[180:183], v[204:207], v[80:83]
	v_mfma_f32_16x16x32_bf16 v[68:71], v[172:175], v[212:215], v[68:71]
	v_mfma_f32_16x16x32_bf16 v[64:67], v[180:183], v[212:215], v[64:67]
	s_setprio 2
	s_barrier
; #define PG8_STAGE(bufoff, gbase, voff) do { _Pragma("unroll") for (int _i = 0; _i < 2; ++_i) \
;         __builtin_amdgcn_global_load_lds((const unsigned*)((const char*)(gbase) + (voff)[_i]), (LAS unsigned*)(lds + (bufoff) + ldsw + _i * 8192), 16, 0, 0); } while (0)
; #define PG8_LDA(dst, b, h) do { _Pragma("unroll") for (int m = 0; m < 4; ++m) _Pragma("unroll") for (int k = 0; k < 2; ++k) dst[m][k] = *(const LAS bf16x8*)(lds + PG8_SA(b, h) + aoff + m * 2048 + k * 1024); } while (0)
; #define PG8_MMA(ai, bj, At, Bt) do { __builtin_amdgcn_s_setprio(1); _Pragma("unroll") for (int m = 0; m < 4; ++m) _Pragma("unroll") for (int n = 0; n < 2; ++n) _Pragma("unroll") for (int k = 0; k < 2; ++k) \
;         acc[ai][bj][m][n] = __builtin_amdgcn_mfma_f32_16x16x32_bf16(Bt[n][k], At[m][k], acc[ai][bj][m][n], 0, 0, 0); __builtin_amdgcn_s_setprio(0); } while (0)
; #define PG8_WAIT_V(n) asm volatile("s_waitcnt vmcnt(" #n ")" ::: "memory")
; #define PG8_WAIT_L(n) asm volatile("s_waitcnt lgkmcnt(" #n ")" ::: "memory")
; #define PG8_BAR __builtin_amdgcn_s_barrier()
; #define PG8_SCHED __builtin_amdgcn_sched_barrier(0)
; template <class Epi, class Sched>
; __device__ __forceinline__ void gemm_phase(LAS unsigned char* lds, const Gemm g, const Sched& S, const Epi& E) {
;     ...
;             PG8_LDA(At, 1, 1); PG8_STAGE(PG8_SB(1, 0), b3, voffB); PG8_STAGE(PG8_SB(1, 1), b3 + hstepB, voffB); PG8_STAGE(PG8_SA(1, 0), a3, voffA);
;             PG8_WAIT_V(8); PG8_WAIT_L(0); PG8_BAR; PG8_MMA(1, 0, At, B0); PG8_MMA(1, 1, At, B1); PG8_BAR; PG8_SCHED;
;         }
;         if (wr == 0) PG8_BAR;
	s_add_i32 s2, s22, s47
	v_lshl_add_u64 v[150:151], v[150:151], 0, s[8:9]
	s_mov_b32 m0, s2
	ds_read_b128 v[184:187], v155 offset:49152
	ds_read_b128 v[188:191], v155 offset:50176
	ds_read_b128 v[192:195], v155 offset:51200
	ds_read_b128 v[196:199], v155 offset:52224
	ds_read_b128 v[200:203], v155 offset:53248
	ds_read_b128 v[204:207], v155 offset:54272
	ds_read_b128 v[208:211], v155 offset:55296
	ds_read_b128 v[212:215], v155 offset:56320
	global_load_lds_dwordx4 v[150:151], off
	s_add_i32 m0, s2, 0x2000
	s_add_u32 s2, s40, 0x80080
	v_lshl_add_u64 v[150:151], v[216:217], 0, s[8:9]
	s_addc_u32 s3, s41, 0
	s_add_i32 s22, s23, s47
	global_load_lds_dwordx4 v[150:151], off
	v_lshl_add_u64 v[150:151], s[2:3], 0, v[132:133]
	s_mov_b32 m0, s22
	s_nop 0
	global_load_lds_dwordx4 v[150:151], off
	v_lshl_add_u64 v[150:151], s[2:3], 0, v[128:129]
	s_add_i32 m0, s22, 0x2000
	s_nop 0
	global_load_lds_dwordx4 v[150:151], off
	v_lshl_add_u64 v[150:151], v[218:219], 0, s[8:9]
	s_mov_b32 m0, s52
	s_nop 0
	global_load_lds_dwordx4 v[150:151], off
	v_lshl_add_u64 v[150:151], v[220:221], 0, s[8:9]
	s_mov_b32 m0, s53
	s_nop 0
	global_load_lds_dwordx4 v[150:151], off
	s_waitcnt vmcnt(8)
	s_waitcnt lgkmcnt(0)
	s_barrier
	s_setprio 1
	s_waitcnt lgkmcnt(0)
	v_mfma_f32_16x16x32_bf16 v[60:63], v[146:149], v[184:187], v[60:63]
	v_mfma_f32_16x16x32_bf16 v[56:59], v[160:163], v[184:187], v[56:59]
	v_mfma_f32_16x16x32_bf16 v[44:47], v[146:149], v[192:195], v[44:47]
	v_mfma_f32_16x16x32_bf16 v[40:43], v[160:163], v[192:195], v[40:43]
	v_mfma_f32_16x16x32_bf16 v[28:31], v[146:149], v[200:203], v[28:31]
	v_mfma_f32_16x16x32_bf16 v[24:27], v[160:163], v[200:203], v[24:27]
	v_mfma_f32_16x16x32_bf16 v[12:15], v[146:149], v[208:211], v[12:15]
	v_mfma_f32_16x16x32_bf16 v[8:11], v[160:163], v[208:211], v[8:11]
	v_mfma_f32_16x16x32_bf16 v[60:63], v[156:159], v[188:191], v[60:63]
	v_mfma_f32_16x16x32_bf16 v[56:59], v[164:167], v[188:191], v[56:59]
	v_mfma_f32_16x16x32_bf16 v[44:47], v[156:159], v[196:199], v[44:47]
	v_mfma_f32_16x16x32_bf16 v[40:43], v[164:167], v[196:199], v[40:43]
	v_mfma_f32_16x16x32_bf16 v[28:31], v[156:159], v[204:207], v[28:31]
	v_mfma_f32_16x16x32_bf16 v[24:27], v[164:167], v[204:207], v[24:27]
	v_mfma_f32_16x16x32_bf16 v[12:15], v[156:159], v[212:215], v[12:15]
	v_mfma_f32_16x16x32_bf16 v[8:11], v[164:167], v[212:215], v[8:11]
	s_setprio 0
	s_setprio 1
	v_mfma_f32_16x16x32_bf16 v[52:55], v[168:171], v[184:187], v[52:55]
	v_mfma_f32_16x16x32_bf16 v[48:51], v[176:179], v[184:187], v[48:51]
	v_mfma_f32_16x16x32_bf16 v[36:39], v[168:171], v[192:195], v[36:39]
	v_mfma_f32_16x16x32_bf16 v[32:35], v[176:179], v[192:195], v[32:35]
	v_mfma_f32_16x16x32_bf16 v[20:23], v[168:171], v[200:203], v[20:23]
	v_mfma_f32_16x16x32_bf16 v[16:19], v[176:179], v[200:203], v[16:19]
	v_mfma_f32_16x16x32_bf16 v[4:7], v[168:171], v[208:211], v[4:7]
	v_mfma_f32_16x16x32_bf16 v[0:3], v[176:179], v[208:211], v[0:3]
	v_mfma_f32_16x16x32_bf16 v[52:55], v[172:175], v[188:191], v[52:55]
	v_mfma_f32_16x16x32_bf16 v[48:51], v[180:183], v[188:191], v[48:51]
	v_mfma_f32_16x16x32_bf16 v[36:39], v[172:175], v[196:199], v[36:39]
	v_mfma_f32_16x16x32_bf16 v[32:35], v[180:183], v[196:199], v[32:35]
	v_mfma_f32_16x16x32_bf16 v[20:23], v[172:175], v[204:207], v[20:23]
	v_mfma_f32_16x16x32_bf16 v[16:19], v[180:183], v[204:207], v[16:19]
	v_mfma_f32_16x16x32_bf16 v[4:7], v[172:175], v[212:215], v[4:7]
	v_mfma_f32_16x16x32_bf16 v[0:3], v[180:183], v[212:215], v[0:3]
	s_setprio 2
	s_barrier
	s_add_i32 s61, s61, 2
	s_add_u32 s38, s38, 0x100
	s_addc_u32 s39, s39, 0
	s_add_u32 s59, s59, 0x100
	s_addc_u32 s60, s60, 0
	s_cmp_gt_u32 s61, 29
	s_cbranch_scc0 .LBB0_883
	s_and_b64 vcc, exec, s[10:11]
	s_cbranch_vccz .LBB0_886
	s_barrier
